# v17: v16 + next key tile's global loads issued before the end-of-tile barrier (right after the staging stores) instead of at the loop top
# speedup vs baseline: 1.0078x; 1.0006x over previous
.LBB0_47:
	s_add_i32 s22, s22, 64
	s_add_u32 s50, s50, 0x60000
	s_addc_u32 s51, s51, 0
	s_add_i32 s10, s10, 1
	s_mul_i32 s23, s4, 0x60000
	s_cmp_ge_u32 s10, s4
	s_cbranch_scc1 .Lle_no_c1
	s_waitcnt lgkmcnt(0)
	v_lshl_add_u64 v[82:83], v[160:161], 0, s[50:51]
	v_lshl_add_u64 v[84:85], v[148:149], 0, s[50:51]
	global_load_dwordx4 v[114:117], v[82:83], off
	global_load_dwordx4 v[118:121], v[84:85], off
	v_lshl_add_u64 v[82:83], v[146:147], 0, s[50:51]
	global_load_dwordx4 v[122:125], v[82:83], off
.Lle_no_c1:
	s_cmp_lg_u32 s23, s50
	s_waitcnt lgkmcnt(0)
	s_barrier
	s_cbranch_scc0 .Lfo_out_c1
	s_cmp_lt_u32 s10, s4
	s_cselect_b64 s[60:61], -1, 0
	s_branch .LBB0_36

.LBB0_62:
	s_add_i32 s10, s10, 64
	s_add_u32 s60, s60, 0x60000
	s_addc_u32 s61, s61, 0
	s_add_i32 s22, s22, 1
	s_cmp_ge_u32 s22, s4
	s_cbranch_scc1 .Lle_no_c2
	s_waitcnt lgkmcnt(0)
	v_lshl_add_u64 v[82:83], v[150:151], 0, s[60:61]
	v_lshl_add_u64 v[84:85], v[148:149], 0, s[60:61]
	global_load_dwordx4 v[122:125], v[82:83], off
	global_load_dwordx4 v[134:137], v[84:85], off
	v_lshl_add_u64 v[82:83], v[146:147], 0, s[60:61]
	global_load_dwordx4 v[138:141], v[82:83], off
.Lle_no_c2:
	s_cmp_lg_u32 s50, s60
	s_waitcnt lgkmcnt(0)
	s_barrier
	s_cbranch_scc0 .Lfo_out_c2
	s_cmp_lt_u32 s22, s4
	s_cselect_b64 s[62:63], -1, 0
	s_branch .LBB0_51

.LBB0_77:
	s_add_i32 s22, s22, 64
	s_mov_b64 s[28:29], 0x60000
	s_add_i32 s4, s4, 1
	v_lshl_add_u64 v[164:165], v[164:165], 0, s[28:29]
	v_lshl_add_u64 v[162:163], v[162:163], 0, s[28:29]
	v_lshl_add_u64 v[160:161], v[160:161], 0, s[28:29]
	s_cmp_ge_u32 s4, s5
	s_cbranch_scc1 .Lle_no_c3
	s_waitcnt lgkmcnt(0)
	v_lshl_add_u64 v[82:83], v[160:161], 0, s[36:37]
	global_load_dwordx4 v[114:117], v[82:83], off
	v_lshl_add_u64 v[82:83], v[162:163], 0, s[36:37]
	global_load_dwordx4 v[118:121], v[82:83], off
	v_lshl_add_u64 v[82:83], v[164:165], 0, s[36:37]
	global_load_dwordx4 v[122:125], v[82:83], off
.Lle_no_c3:
	s_cmp_lg_u32 s10, s22
	s_waitcnt lgkmcnt(0)
	s_barrier
	s_cbranch_scc0 .Lfo_out_c3
	s_cmp_lt_u32 s4, s5
	s_cselect_b64 s[28:29], -1, 0
	s_branch .LBB0_66

.LBB0_92:
	s_add_i32 s4, s4, 64
	s_mov_b64 s[28:29], 0x60000
	s_add_i32 s22, s22, 1
	v_lshl_add_u64 v[146:147], v[146:147], 0, s[28:29]
	v_lshl_add_u64 v[148:149], v[148:149], 0, s[28:29]
	v_lshl_add_u64 v[150:151], v[150:151], 0, s[28:29]
	s_cmp_ge_u32 s22, s5
	s_cbranch_scc1 .Lle_no_c4
	s_waitcnt lgkmcnt(0)
	v_lshl_add_u64 v[82:83], v[150:151], 0, s[36:37]
	global_load_dwordx4 v[114:117], v[82:83], off
	v_lshl_add_u64 v[82:83], v[148:149], 0, s[36:37]
	global_load_dwordx4 v[130:133], v[82:83], off
	v_lshl_add_u64 v[82:83], v[146:147], 0, s[36:37]
	global_load_dwordx4 v[138:141], v[82:83], off
.Lle_no_c4:
	s_cmp_lg_u32 s10, s4
	s_waitcnt lgkmcnt(0)
	s_barrier
	s_cbranch_scc0 .Lfo_out_c4
	s_cmp_lt_u32 s22, s5
	s_cselect_b64 s[28:29], -1, 0
	s_branch .LBB0_81
